# v019 plus indexer step loop: waves 4-7 delayed by s_sleep 5 after each step barrier so SIMD partners alternate MFMA and VALU
# speedup vs baseline: 1.0030x; 1.0030x over previous
; #define LAS __attribute__((address_space(3)))
; __device__ __forceinline__ void indexer_phase_wg(const bf16_t* qkv, const float* wi32, float* scores, LAS unsigned char* lds, int bid, int G, int tid, int wave, int lane) {
;     ...
;         for (int st = 0; st < nstep; ++st) {
;             if (st + 1 < nstep) { const int r0 = 128 * (st + 1);
;                 kreg0 = *(const u32x4*)(kg + (size_t)min(r0, lastrow - srow) * LDQ); kreg1 = *(const u32x4*)(kg + (size_t)min(r0 + 64, lastrow - srow) * LDQ); }
;             const LAS unsigned char* buf = lds + (st & 1) * 16384;
; #pragma unroll
;             for (int sub = 0; sub < 4; ++sub) {
;                 const int k0 = 128 * st + 32 * sub;
;                 {
;                     const int key = k0 + r32, lrow = 32 * (sub & 1) + r32;
;                     const LAS unsigned char* img = buf + (sub >> 1) * 8192;
;                     bf16x8 kf[4];
; #pragma unroll
;                     for (int ks = 0; ks < 4; ++ks) kf[ks] = *(const LAS bf16x8*)(img + lrow * 128 + (((2 * ks + hi) ^ ((lrow >> 1) & 7)) * 16));
.LBB0_442:
	v_readlane_b32 s98, v250, 4
	s_cmp_lt_u32 s98, 4
	s_cbranch_scc1 .Lidx_nostag
	s_sleep 5
